# v46 with s_sleep removed from the two steady-state barrier poll loops (faster re-poll)
# baseline (speedup 1.0000x reference)
.LBB0_1167:
	s_and_b32 s11, s2, 0xff
	s_mov_b64 s[26:27], -1
	s_cmp_lg_u32 s11, 0
	s_mov_b64 s[40:41], -1
	s_cbranch_scc1 .LBB0_1170
	v_readlane_b32 s28, v254, 11
	v_readlane_b32 s29, v254, 12
	s_nop 4
	global_load_dword v0, v173, s[28:29] sc1
	s_waitcnt vmcnt(0)
	v_cmp_eq_u32_e32 vcc, 0, v0
	s_cbranch_vccnz .LBB0_1172
	s_mov_b64 s[40:41], 0
	s_mov_b64 s[28:29], -1
